# v31 + prep gate weights resident across items and the gate loop waiting only on LDS (no VMEM wait inside the loop)
# speedup vs baseline: 1.0027x; 1.0010x over previous
; LPHASE void phase_gla_prep(char* ws_, const float* x_, float* out_, const float* meta_, int nseq_, char* lds) {
;     ...
;     { bf16_t* dst = (bf16_t*)(gp + GP_VT) + ((size_t)ch * 4 + hd) * 256 * 64;
; #pragma unroll
;       for (int q = 0; q < 4; ++q) { const int i8 = (tid & 7) * 8, c = (tid >> 3) + 64 * q; bf16x8 w;
; #pragma unroll
;         for (int e = 0; e < 8; ++e) w[e] = (short)vt[(i8 + e) * 264 + c];
;         *(bf16x8*)(dst + c * 64 + i8) = w; } }
;     { float wf[16], wb[16];
; #pragma unroll
;       for (int k = 0; k < 16; ++k) { wf[k] = smg[S_WAF + k * 512 + hd * 128 + d]; wb[k] = smg[S_WAB + k * 512 + hd * 128 + d]; }
;       const float bfv = smg[S_BAF + hd * 128 + d], bbv = smg[S_BAB + hd * 128 + d];
.LBB0_505:
	s_or_b64 exec, exec, s[28:29]
	s_ashr_i32 s1, s0, 31
	s_lshl_b64 s[38:39], s[0:1], 2
	s_or_b32 s38, s38, s30
	v_lshlrev_b32_e32 v0, 3, v16
	s_lshl_b64 s[2:3], s[38:39], 15
	s_add_u32 s0, s52, s2
	v_and_b32_e32 v0, 56, v0
	s_addc_u32 s1, s53, s3
	v_ashrrev_i32_e32 v1, 3, v16
	v_lshlrev_b32_e32 v132, 1, v0
	v_lshl_add_u64 v[8:9], s[0:1], 0, v[132:133]
	v_mul_u32_u24_e32 v4, 0x210, v0
	v_lshlrev_b32_e32 v5, 1, v1
	v_readlane_b32 s0, v254, 31
	s_waitcnt lgkmcnt(0)
	s_barrier
	v_add3_u32 v4, s0, v5, v4
	ds_read_u16 v5, v4 offset:3168
	ds_read_u16 v6, v4 offset:3696
	ds_read_u16 v12, v4 offset:3296
	ds_read_u16 v13, v4 offset:3824
	ds_read_u16 v14, v4 offset:3424
	ds_read_u16 v15, v4 offset:3952
	ds_read_u16 v17, v4 offset:4080
	ds_read_u16 v22, v4 offset:3552
	s_waitcnt lgkmcnt(6)
	v_perm_b32 v7, v6, v5, s84
	ds_read_u16 v5, v4 offset:2112
	ds_read_u16 v6, v4 offset:2640
	ds_read_u16 v18, v4 offset:2240
	ds_read_u16 v19, v4 offset:2768
	ds_read_u16 v23, v4 offset:2368
	ds_read_u16 v24, v4 offset:2896
	ds_read_u16 v25, v4 offset:3024
	ds_read_u16 v60, v4 offset:2496
	s_waitcnt lgkmcnt(6)
	v_perm_b32 v6, v6, v5, s84
	ds_read_u16 v5, v4 offset:1056
	ds_read_u16 v10, v4 offset:1584
	ds_read_u16 v61, v4 offset:1184
	ds_read_u16 v62, v4 offset:1712
	ds_read_u16 v63, v4 offset:1312
	ds_read_u16 v64, v4 offset:1840
	ds_read_u16 v65, v4 offset:1968
	ds_read_u16 v66, v4 offset:1440
	v_lshlrev_b32_e32 v20, 6, v1
	s_waitcnt lgkmcnt(6)
	v_perm_b32 v5, v10, v5, s84
	ds_read_u16 v10, v4
	ds_read_u16 v11, v4 offset:528
	ds_read_u16 v67, v4 offset:128
	ds_read_u16 v68, v4 offset:656
	ds_read_u16 v69, v4 offset:256
	ds_read_u16 v70, v4 offset:784
	ds_read_u16 v71, v4 offset:912
	ds_read_u16 v72, v4 offset:384
	v_ashrrev_i32_e32 v21, 31, v20
	s_waitcnt lgkmcnt(6)
	v_perm_b32 v4, v11, v10, s84
	v_lshl_add_u64 v[10:11], v[20:21], 1, v[8:9]
	global_store_dwordx4 v[10:11], v[4:7], off
	s_add_i32 s0, s12, 0x980
	v_mov_b32_e32 v84, 0
	v_perm_b32 v6, v19, v18, s84
	v_add_u32_e32 v18, 0x1000, v20
	v_ashrrev_i32_e32 v19, 31, v18
	v_perm_b32 v7, v13, v12, s84
	v_perm_b32 v5, v62, v61, s84
	s_waitcnt lgkmcnt(4)
	v_perm_b32 v4, v68, v67, s84
	v_lshl_add_u64 v[10:11], v[18:19], 1, v[8:9]
	global_store_dwordx4 v[10:11], v[4:7], off
	v_add_u32_e32 v10, 0x2000, v20
	v_ashrrev_i32_e32 v11, 31, v10
	v_perm_b32 v7, v15, v14, s84
	v_perm_b32 v6, v24, v23, s84
	v_perm_b32 v5, v64, v63, s84
	s_waitcnt lgkmcnt(2)
	v_perm_b32 v4, v70, v69, s84
	v_lshl_add_u64 v[10:11], v[10:11], 1, v[8:9]
	global_store_dwordx4 v[10:11], v[4:7], off
	v_add_u32_e32 v10, 0x3000, v20
	v_ashrrev_i32_e32 v11, 31, v10
	v_perm_b32 v7, v17, v22, s84
	v_perm_b32 v6, v25, v60, s84
	v_perm_b32 v5, v65, v66, s84
	s_waitcnt lgkmcnt(0)
	v_perm_b32 v4, v71, v72, s84
	v_lshl_add_u64 v[8:9], v[10:11], 1, v[8:9]
	global_store_dwordx4 v[8:9], v[4:7], off
	s_cmp_eq_u32 s32, 1
	s_cbranch_scc1 .Lw_skip
	s_mov_b32 s32, 1
	v_mov_b32_e32 v25, v133
	s_nop 0
	v_or_b32_e32 v4, s0, v2
	v_lshlrev_b32_e32 v132, 2, v4
	v_lshl_add_u64 v[22:23], s[34:35], 0, v[132:133]
	s_add_i32 s0, s12, 0x2b80
	v_add_co_u32_e32 v70, vcc, s4, v22
	v_or_b32_e32 v5, s0, v2
	s_nop 0
	v_addc_co_u32_e32 v71, vcc, 0, v23, vcc
	v_lshlrev_b32_e32 v24, 2, v5
	v_add_co_u32_e32 v6, vcc, s72, v22
	v_lshl_add_u64 v[60:61], s[34:35], 0, v[24:25]
	s_nop 0
	v_addc_co_u32_e32 v7, vcc, 0, v23, vcc
	v_add_co_u32_e32 v72, vcc, s4, v60
	s_add_i32 s0, s12, 0x2980
	s_nop 0
	v_addc_co_u32_e32 v73, vcc, 0, v61, vcc
	v_add_co_u32_e32 v4, vcc, s72, v60
	s_addk_i32 s12, 0x4b80
	s_nop 0
	v_addc_co_u32_e32 v5, vcc, 0, v61, vcc
	v_add_co_u32_e32 v14, vcc, s92, v22
	v_or_b32_e32 v25, s12, v2
	s_nop 0
	v_addc_co_u32_e32 v15, vcc, 0, v23, vcc
	v_add_co_u32_e32 v74, vcc, s73, v22
	global_load_dword v172, v[6:7], off offset:-4096
	global_load_dword v173, v[4:5], off offset:-4096
	global_load_dword v176, v[6:7], off
	global_load_dword v177, v[4:5], off
	global_load_dword v179, v[4:5], off offset:2048
	global_load_dword v180, v[14:15], off offset:-4096
	s_nop 0
	global_load_dword v184, v[14:15], off
	global_load_dword v178, v[6:7], off offset:2048
	v_addc_co_u32_e32 v75, vcc, 0, v23, vcc
	v_add_co_u32_e32 v76, vcc, s73, v60
	v_or_b32_e32 v17, s0, v2
	s_nop 0
	v_addc_co_u32_e32 v77, vcc, 0, v61, vcc
	v_add_co_u32_e32 v8, vcc, s92, v60
	v_lshlrev_b32_e32 v17, 2, v17
	s_nop 0
	v_addc_co_u32_e32 v9, vcc, 0, v61, vcc
	v_add_co_u32_e32 v78, vcc, s69, v22
	s_movk_i32 s0, 0x2040
	s_nop 0
	v_addc_co_u32_e32 v79, vcc, 0, v23, vcc
	v_add_co_u32_e32 v80, vcc, s69, v60
	s_mov_b32 s12, 0
	s_nop 0
	v_addc_co_u32_e32 v81, vcc, 0, v61, vcc
	global_load_dword v181, v[8:9], off offset:-4096
	global_load_dword v185, v[8:9], off
	global_load_dword v187, v[8:9], off offset:2048
	s_nop 0
	global_load_dword v188, v[78:79], off offset:-4096
	global_load_dword v189, v[80:81], off offset:-4096
	global_load_dword v192, v[78:79], off
	global_load_dword v194, v[78:79], off offset:2048
	global_load_dword v186, v[14:15], off offset:2048
	v_add_co_u32_e32 v78, vcc, s74, v22
	global_load_dword v193, v[80:81], off
	global_load_dword v195, v[80:81], off offset:2048
	v_addc_co_u32_e32 v79, vcc, 0, v23, vcc
	v_add_co_u32_e32 v82, vcc, s74, v60
	s_nop 1
	v_addc_co_u32_e32 v83, vcc, 0, v61, vcc
	v_add_co_u32_e32 v80, vcc, s75, v22
	s_nop 1
	v_addc_co_u32_e32 v81, vcc, 0, v23, vcc
	v_add_co_u32_e32 v60, vcc, s75, v60
	global_load_dword v174, v[70:71], off offset:2048
	s_nop 0
	global_load_dword v175, v[72:73], off offset:2048
	s_nop 0
	global_load_dword v182, v[74:75], off offset:2048
	global_load_dword v183, v[76:77], off offset:2048
	global_load_dword v190, v[78:79], off offset:2048
	global_load_dword v191, v[82:83], off offset:2048
	global_load_dword v196, v[80:81], off
	global_load_dword v198, v[80:81], off offset:2048
	v_lshlrev_b32_e32 v79, 2, v25
	v_addc_co_u32_e32 v61, vcc, 0, v61, vcc
	global_load_dword v168, v132, s[34:35]
	global_load_dword v169, v24, s[34:35]
	global_load_dword v171, v24, s[34:35] offset:2048
	global_load_dword v170, v132, s[34:35] offset:2048
	s_nop 0
	global_load_dword v197, v[60:61], off
	global_load_dword v199, v[60:61], off offset:2048
	global_load_dword v200, v17, s[34:35]
	s_nop 0
	global_load_dword v201, v79, s[34:35]
	s_waitcnt vmcnt(0)

; LPHASE void phase_gla_prep(char* ws_, const float* x_, float* out_, const float* meta_, int nseq_, char* lds) {
;     ...
; #pragma unroll 2
;       for (int ii = 0; ii < 16; ++ii) { const int i = ig * 16 + ii; float sf = bfv, sb = bbv; const float* a = af + i * 32;
; #pragma unroll
;         for (int k = 0; k < 16; ++k) { sf += a[k] * wf[k]; sb += a[16 + k] * wb[k]; }
;         float lf = (fminf(sf, 0.f) - __logf(1.f + __expf(-fabsf(sf)))) * (1.f / 16.f), lb = (fminf(sb, 0.f) - __logf(1.f + __expf(-fabsf(sb)))) * (1.f / 16.f);
;         if (ismeta && i >= 16) { lf = 0.f; lb = 0.f; }
;         lgF[i * LGP + d] = lf; lgB[i * LGP + d] = lb; tfl += lf; tbl += lb; }
;       tot[ig * 128 + d] = tfl; tot[512 + ig * 128 + d] = tbl;
;     }
;     __syncthreads();
;     { const float t0 = tot[d], t1 = tot[128 + d], t2 = tot[256 + d], t3 = tot[384 + d];
;       const float u0 = tot[512 + d], u1 = tot[640 + d], u2 = tot[768 + d], u3 = tot[896 + d];
;       const float blF = (t0 + t1) + (t2 + t3), brF = t0 + t1, blB = (u0 + u1) + (u2 + u3), brB = u2 + u3;
;       const float offF = ig == 0 ? 0.f : ig == 1 ? t0 : ig == 2 ? t0 + t1 : (t0 + t1) + t2;
;       const float offB = ig == 3 ? 0.f : ig == 2 ? u3 : ig == 1 ? u2 + u3 : (u1 + u2) + u3;
;       const float myB = ig == 0 ? u0 : ig == 1 ? u1 : ig == 2 ? u2 : u3;
.LBB0_506:
	v_add_u32_e32 v85, s12, v80
	v_add_u32_e32 v96, 0x10200, v85
	ds_read_b128 v[100:103], v96
	ds_read_b128 v[104:107], v96 offset:64
	ds_read_b128 v[108:111], v96 offset:16
	ds_read_b128 v[112:115], v96 offset:80
	ds_read_b128 v[116:119], v96 offset:32
	ds_read_b128 v[120:123], v96 offset:96
	ds_read_b128 v[124:127], v96 offset:48
	ds_read_b128 v[128:131], v96 offset:112
	ds_read_b128 v[136:139], v96 offset:128
	ds_read_b128 v[140:143], v96 offset:192
	ds_read_b128 v[144:147], v96 offset:144
	ds_read_b128 v[148:151], v96 offset:208
	ds_read_b128 v[152:155], v96 offset:160
	ds_read_b128 v[156:159], v96 offset:224
	ds_read_b128 v[160:163], v96 offset:176
	ds_read_b128 v[164:167], v96 offset:240
	s_waitcnt lgkmcnt(0)
	s_addk_i32 s12, 0x100
	v_fma_f32 v94, v168, v100, v200
	v_fmac_f32_e32 v94, v170, v101
	v_fmac_f32_e32 v94, v172, v102
	v_fmac_f32_e32 v94, v174, v103
	v_fma_f32 v95, v169, v104, v201
	v_fmac_f32_e32 v95, v171, v105
	v_fmac_f32_e32 v95, v173, v106
	v_fmac_f32_e32 v95, v175, v107
	v_fmac_f32_e32 v94, v176, v108
	v_fmac_f32_e32 v94, v178, v109
	v_fmac_f32_e32 v94, v180, v110
	v_fmac_f32_e32 v94, v182, v111
	v_fmac_f32_e32 v95, v177, v112
	v_fmac_f32_e32 v95, v179, v113
	v_fmac_f32_e32 v95, v181, v114
	v_fmac_f32_e32 v95, v183, v115
	v_fma_f32 v94, v184, v116, v94
	v_fmac_f32_e32 v94, v186, v117
	v_fma_f32 v90, v185, v120, v95
	v_fmac_f32_e32 v90, v187, v121
	v_fma_f32 v91, v188, v118, v94
	v_fmac_f32_e32 v91, v190, v119
	v_fma_f32 v94, v189, v122, v90
	v_fmac_f32_e32 v94, v191, v123
	v_fma_f32 v95, v192, v124, v91
	v_fmac_f32_e32 v95, v194, v125
	v_fma_f32 v90, v193, v128, v94
	v_fmac_f32_e32 v90, v195, v129
	v_fma_f32 v88, v196, v126, v95
	v_fmac_f32_e32 v88, v198, v127
	v_fma_f32 v86, v197, v130, v90
	v_fmac_f32_e32 v86, v199, v131
	v_min_f32_e32 v87, 0, v88
	v_mul_f32_e64 v88, |v88|, s6
	v_exp_f32_e32 v88, v88
	s_nop 0
	v_add_f32_e32 v88, 1.0, v88
	v_log_f32_e32 v88, v88
	s_nop 0
	v_mul_f32_e32 v89, 0x3f317217, v88
	v_fma_f32 v89, v88, s13, -v89
	v_fmac_f32_e32 v89, 0x3377d1cf, v88
	v_fmac_f32_e32 v89, 0x3f317217, v88
	v_mov_b32_e32 v88, v89
	v_sub_f32_e32 v87, v87, v88
	v_min_f32_e32 v88, 0, v86
	v_mul_f32_e64 v86, |v86|, s6
	v_exp_f32_e32 v86, v86
	v_mul_f32_e32 v87, 0x3d800000, v87
	v_add_f32_e32 v86, 1.0, v86
	v_log_f32_e32 v86, v86
	s_nop 0
	v_mul_f32_e32 v89, 0x3f317217, v86
	v_fma_f32 v89, v86, s13, -v89
	v_fmac_f32_e32 v89, 0x3377d1cf, v86
	v_fmac_f32_e32 v89, 0x3f317217, v86
	v_mov_b32_e32 v86, v89
	v_sub_f32_e32 v86, v88, v86
	v_cmp_lt_i32_e32 vcc, 15, v82
	v_mul_f32_e32 v86, 0x3d800000, v86
	s_and_b64 s[0:1], s[26:27], vcc
	v_cndmask_b32_e64 v86, v86, 0, s[0:1]
	v_cndmask_b32_e64 v87, v87, 0, s[0:1]
	ds_write_b32 v81, v87
	ds_write_b32 v81, v86 offset:33024
	v_add_f32_e32 v84, v84, v86
	v_add_f32_e32 v83, v83, v87
	v_fma_f32 v94, v168, v136, v200
	v_fmac_f32_e32 v94, v170, v137
	v_fmac_f32_e32 v94, v172, v138
	v_fmac_f32_e32 v94, v174, v139
	v_fma_f32 v95, v169, v140, v201
	v_fmac_f32_e32 v95, v171, v141
	v_fmac_f32_e32 v95, v173, v142
	v_fmac_f32_e32 v95, v175, v143
	v_fmac_f32_e32 v94, v176, v144
	v_fmac_f32_e32 v94, v178, v145
	v_fmac_f32_e32 v94, v180, v146
	v_fmac_f32_e32 v94, v182, v147
	v_fmac_f32_e32 v95, v177, v148
	v_fmac_f32_e32 v95, v179, v149
	v_fmac_f32_e32 v95, v181, v150
	v_fmac_f32_e32 v95, v183, v151
	v_fma_f32 v94, v184, v152, v94
	v_fmac_f32_e32 v94, v186, v153
	v_fma_f32 v90, v185, v156, v95
	v_fmac_f32_e32 v90, v187, v157
	v_fma_f32 v91, v188, v154, v94
	v_fmac_f32_e32 v91, v190, v155
	v_fma_f32 v94, v189, v158, v90
	v_fmac_f32_e32 v94, v191, v159
	v_fma_f32 v95, v192, v160, v91
	v_fmac_f32_e32 v95, v194, v161
	v_fma_f32 v85, v193, v164, v94
	v_fmac_f32_e32 v85, v195, v165
	v_fma_f32 v88, v196, v162, v95
	v_fmac_f32_e32 v88, v198, v163
	v_fma_f32 v85, v197, v166, v85
	v_fmac_f32_e32 v85, v199, v167
	v_mul_f32_e64 v87, |v88|, s6
	v_exp_f32_e32 v87, v87
	v_min_f32_e32 v86, 0, v88
	v_add_f32_e32 v87, 1.0, v87
	v_log_f32_e32 v87, v87
	s_nop 0
	v_mul_f32_e32 v88, 0x3f317217, v87
	v_fma_f32 v88, v87, s13, -v88
	v_fmac_f32_e32 v88, 0x3377d1cf, v87
	v_fmac_f32_e32 v88, 0x3f317217, v87
	v_mov_b32_e32 v87, v88
	v_sub_f32_e32 v86, v86, v87
	v_min_f32_e32 v87, 0, v85
	v_mul_f32_e64 v85, |v85|, s6
	v_exp_f32_e32 v85, v85
	v_mul_f32_e32 v86, 0x3d800000, v86
	v_add_f32_e32 v85, 1.0, v85
	v_log_f32_e32 v85, v85
	s_nop 0
	v_mul_f32_e32 v88, 0x3f317217, v85
	v_fma_f32 v88, v85, s13, -v88
	v_fmac_f32_e32 v88, 0x3377d1cf, v85
	v_fmac_f32_e32 v88, 0x3f317217, v85
	v_mov_b32_e32 v85, v88
	v_sub_f32_e32 v85, v87, v85
	v_cmp_lt_i32_e32 vcc, 14, v82
	v_mul_f32_e32 v85, 0x3d800000, v85
	s_and_b64 s[0:1], s[26:27], vcc
	v_cndmask_b32_e64 v85, v85, 0, s[0:1]
	v_cndmask_b32_e64 v86, v86, 0, s[0:1]
	ds_write_b32 v81, v86 offset:516
	ds_write_b32 v81, v85 offset:33540
	v_add_f32_e32 v83, v83, v86
	v_add_f32_e32 v84, v84, v85
	v_add_u32_e32 v82, 2, v82
	v_add_u32_e32 v81, 0x408, v81
	s_cmpk_eq_i32 s12, 0x800
	s_cbranch_scc0 .LBB0_506
	v_and_b32_e32 v4, 0x3fffff80, v16
	v_lshl_add_u32 v6, v2, 2, s85
	v_lshl_add_u32 v5, v16, 2, s85
	v_lshl_add_u32 v4, v4, 2, v6
	ds_write_b32 v5, v83
	ds_write_b32 v4, v84 offset:2048
	s_waitcnt lgkmcnt(0)
	s_barrier
	ds_read2st64_b32 v[10:11], v6 offset1:2
	ds_read2st64_b32 v[8:9], v6 offset0:4 offset1:6
	ds_read2st64_b32 v[4:5], v6 offset0:8 offset1:10
	ds_read2st64_b32 v[6:7], v6 offset0:12 offset1:14
	s_movk_i32 s0, 0x80
	v_cmp_gt_u32_e32 vcc, s0, v16
	s_movk_i32 s0, 0x7f
	s_waitcnt lgkmcnt(3)
	v_add_f32_e32 v11, v10, v11
	v_cmp_lt_u32_e64 s[0:1], s0, v16
	v_mov_b32_e32 v13, 0
	s_and_saveexec_b64 s[26:27], s[0:1]
	s_cbranch_execz .LBB0_513
	v_cmp_lt_i32_e64 s[0:1], 1, v49
	s_mov_b64 s[28:29], 0
	s_and_saveexec_b64 s[30:31], s[0:1]
	s_xor_b64 s[42:43], exec, s[30:31]
	s_cbranch_execnz .LBB0_527
	s_or_saveexec_b64 s[42:43], s[42:43]
	v_mov_b32_e32 v13, v11
	s_xor_b64 exec, exec, s[42:43]
	s_cbranch_execnz .LBB0_530
